# prep: next-pair loads waited only at register hand-over (no mid-iteration vmcnt(0)), prefetch block behind MFMA issue; prep tail rewritten with 4 interleaved DPP wave reductions
# speedup vs baseline: 1.1036x; 1.0265x over previous
; DEV void prep_load(PRef p, const PrepConst& pc, int b, int d, int s, PrepRaw& rw) {
;   bool isctx = s < 256;
;   int pos = isctx ? (d ? 255 - s : s) : (d ? 2047 - (s - 256) : s - 256);
;   int seglen = isctx ? 256 : 2048;
;   int row = b * TPB + (isctx ? 0 : 256) + pos;
;   rw.row = row;
;   bool hp = pos > 0, hn = pos < seglen - 1;
;   const bf16* z = p.ZA + (size_t)row * 1792;
;   const bf16* zpp = hp ? z - 1792 : z;
;   const bf16* znp = hn ? z + 1792 : z;
;   rw.fp = hp ? 1.f : 0.f;
;   rw.fn = hn ? 1.f : 0.f;
; #pragma unroll
;   for (int i = 0; i < 5; i++) {
;     int col = pc.cols[i];
;     rw.zc[i] = z[col];
;     rw.zp[i] = zpp[col];
;     rw.zn[i] = znp[col];
;   }
; }
; __device__ void scan_chain(PRef p, int l, int chain, ScanSm* sm) {
;     ...
;     float Dprev = 1.f;
;     PrepRaw rwA, rwB, rnA, rnB;
;     prep_load(p, pc, b, d, i, rwA);
;     prep_load(p, pc, b, d, i + 1, rwB);
; #pragma unroll 1
;     while (c < 144) {
;       int i2 = i + 2, c2 = c;
;       if (i2 >= base + 8) { i2 = base; c2 = c + 1; }
;       if (c2 < 144) {
;         prep_load(p, pc, b, d, c2 * 16 + i2, rnA);
;         prep_load(p, pc, b, d, c2 * 16 + i2 + 1, rnB);
;       }
;       if (i == base) Dprev = 1.f;
;       prep_compute2(p, pc, rwA, rwB, h, d, &sm->rec[c & 1][i], &sm->rec[c & 1][i + 1], stw, lane, Dprev);
;       if (c2 != c) __syncthreads();
;       rwA = rnA;
;       rwB = rnB;
;       i = i2;
;       c = c2;
;     }
.LBB0_580:
	s_or_saveexec_b64 s[8:9], s[8:9]
	v_mov_b32_e32 v2, 0x7ff
	v_mov_b32_e32 v9, 0x100
	s_xor_b64 exec, exec, s[8:9]
	v_add_u32_e32 v1, -15, v96
	v_sub_u32_e32 v2, 0x10e, v96
	v_cndmask_b32_e64 v1, v2, v1, s[4:5]
	v_mov_b32_e32 v2, 0xff
	v_mov_b32_e32 v9, 0
	s_or_b64 exec, exec, s[8:9]
	v_lshlrev_b32_e32 v95, 9, v12
	v_add3_u32 v12, v9, s28, v1
	v_cmp_lt_i32_e32 vcc, 0, v1
	v_cmp_lt_i32_e64 s[8:9], v1, v2
	v_mov_b64_e32 v[98:99], s[70:71]
	v_mad_i64_i32 v[98:99], s[0:1], v12, s94, v[98:99]
	v_cndmask_b32_e64 v101, 0, -1, vcc
	v_cndmask_b32_e32 v100, 0, v203, vcc
	v_cndmask_b32_e64 v2, 0, v204, s[8:9]
	v_lshl_add_u64 v[100:101], v[98:99], 0, v[100:101]
	v_lshl_add_u64 v[102:103], v[98:99], 0, v[2:3]
	v_mov_b32_e32 v1, v3
	v_lshl_add_u64 v[104:105], v[98:99], 0, v[0:1]
	v_lshl_add_u64 v[106:107], v[100:101], 0, v[0:1]
	v_lshl_add_u64 v[108:109], v[102:103], 0, v[0:1]
	global_load_ushort v160, v[104:105], off
	global_load_ushort v163, v[106:107], off
	global_load_ushort v164, v[108:109], off
	global_load_ushort v158, v[104:105], off offset:1024
	global_load_ushort v161, v[106:107], off offset:1024
	global_load_ushort v162, v[108:109], off offset:1024
	global_load_ushort v153, v[104:105], off offset:2048
	global_load_ushort v155, v[106:107], off offset:2048
	global_load_ushort v157, v[108:109], off offset:2048
	v_mov_b32_e32 v9, v3
	v_lshl_add_u64 v[98:99], v[98:99], 0, v[8:9]
	v_lshl_add_u64 v[100:101], v[100:101], 0, v[8:9]
	v_lshl_add_u64 v[102:103], v[102:103], 0, v[8:9]
	global_load_ushort v151, v[98:99], off offset:3072
	global_load_ushort v154, v[100:101], off offset:3072
	global_load_ushort v159, v[102:103], off offset:3072
	global_load_ushort v150, v[98:99], off offset:3328
	global_load_ushort v152, v[100:101], off offset:3328
	global_load_ushort v156, v[102:103], off offset:3328
	s_lshl_b32 s0, s62, 5
	s_add_u32 s0, s18, s0
	v_cndmask_b32_e64 v146, 0, 1.0, s[10:11]
	s_addc_u32 s1, s19, 0
	s_lshl_b32 s10, s63, 2
	s_add_u32 s22, s0, s10
	v_mov_b32_e32 v4, 1.0
	v_cndmask_b32_e64 v147, 0, 1.0, s[12:13]
	v_cndmask_b32_e64 v148, 0, 1.0, vcc
	v_cndmask_b32_e64 v149, 0, 1.0, s[8:9]
	v_add_u32_e32 v96, -8, v96
	v_lshl_or_b32 v97, v28, 1, v95
	v_cmp_eq_u32_e64 s[8:9], 0, v28
	s_addc_u32 s23, s1, 0
	v_mov_b32_e32 v145, 0
	s_mov_b64 s[26:27], 0
	v_mov_b32_e32 v165, v30
	s_waitcnt vmcnt(0)
	s_branch .LBB0_584
.LBB0_583:
	s_or_b64 exec, exec, s[12:13]
	s_waitcnt vmcnt(2)
	v_mov_b32_e32 v145, v119
	v_mov_b32_e32 v165, v117
	v_mov_b32_e32 v160, v2
	v_mov_b32_e32 v158, v1
	v_mov_b32_e32 v153, v122
	v_mov_b32_e32 v151, v127
	v_mov_b32_e32 v150, v9
	v_mov_b32_e32 v163, v121
	v_mov_b32_e32 v161, v123
	v_mov_b32_e32 v155, v125
	v_mov_b32_e32 v154, v129
	v_mov_b32_e32 v152, v130
	v_mov_b32_e32 v164, v124
	v_mov_b32_e32 v162, v126
	v_mov_b32_e32 v157, v128
	v_mov_b32_e32 v159, v131
	v_mov_b32_e32 v156, v133
	v_mov_b32_e32 v148, v118
	v_mov_b32_e32 v149, v120
	v_mov_b32_e32 v12, v114
	v_mov_b32_e32 v141, v99
	v_mov_b32_e32 v137, v100
	v_mov_b32_e32 v134, v102
	v_mov_b32_e32 v11, v107
	v_mov_b32_e32 v5, v109
	v_mov_b32_e32 v142, v101
	v_mov_b32_e32 v138, v103
	v_mov_b32_e32 v135, v105
	v_mov_b32_e32 v13, v108
	v_mov_b32_e32 v6, v111
	v_mov_b32_e32 v144, v104
	v_mov_b32_e32 v140, v106
	v_mov_b32_e32 v139, v110
	v_mov_b32_e32 v136, v112
	v_mov_b32_e32 v7, v113
	v_mov_b32_e32 v146, v115
	v_mov_b32_e32 v147, v116
	v_mov_b32_e32 v10, v98
	s_andn2_b64 exec, exec, s[26:27]
	s_cbranch_execz .LBB0_605
; DEV float bf2f(bf16 h) { return __uint_as_float(((uint32_t)h) << 16); }
; DEV void wbar() { __builtin_amdgcn_wave_barrier(); }
; DEV void prep_compute2(PRef p, const PrepConst& pc, const PrepRaw& rwA, const PrepRaw& rwB, int h, int d,
;                        ScanRec* rcA, ScanRec* rcB, float* stw, int lane, float& Dprev) {
;   float valsA[5], valsB[5];
; #pragma unroll
;   for (int i = 0; i < 5; i++) {
;     float zc = bf2f(rwA.zc[i]), zp = rwA.fp * bf2f(rwA.zp[i]), zn = rwA.fn * bf2f(rwA.zn[i]);
;     valsA[i] = zc + pc.mup[i] * (zp - zc) + pc.mun[i] * (zn - zc);
;     float zc2 = bf2f(rwB.zc[i]), zp2 = rwB.fp * bf2f(rwB.zp[i]), zn2 = rwB.fn * bf2f(rwB.zn[i]);
;     valsB[i] = zc2 + pc.mup[i] * (zp2 - zc2) + pc.mun[i] * (zn2 - zc2);
;   }
;   float thA = 1.f - __fdividef(2.f, 1.f + __expf(2.f * valsA[3]));
;   float thB = 1.f - __fdividef(2.f, 1.f + __expf(2.f * valsB[3]));
;   bf16* stb = (bf16*)stw;
;   wbar();
;   stb[lane] = f2bf(thA);
;   stb[64 + lane] = f2bf(valsA[4]);
;   stb[128 + lane] = f2bf(thB);
;   stb[192 + lane] = f2bf(valsB[4]);
;   wbar();
;   float wA0 = pc.w0v, wA1 = 0.f, aA0 = pc.a0v, aA1 = 0.f;
;   float wB0 = pc.w0v, wB1 = 0.f, aB0 = pc.a0v, aB1 = 0.f;
;   const uint4* st4 = (const uint4*)stw;
; #pragma unroll
;   for (int g = 0; g < 8; g++) {
;     uint4 tA = st4[g], uA = st4[8 + g], tB = st4[16 + g], uB = st4[24 + g];
;     uint32_t w0 = pc.wu[4 * g], w1 = pc.wu[4 * g + 1], w2 = pc.wu[4 * g + 2], w3 = pc.wu[4 * g + 3];
;     uint32_t u0 = pc.au[4 * g], u1 = pc.au[4 * g + 1], u2 = pc.au[4 * g + 2], u3 = pc.au[4 * g + 3];
;     wA0 = dot2bf(tA.x, w0, wA0); wB0 = dot2bf(tB.x, w0, wB0);
;     wA1 = dot2bf(tA.y, w1, wA1); wB1 = dot2bf(tB.y, w1, wB1);
;     wA0 = dot2bf(tA.z, w2, wA0); wB0 = dot2bf(tB.z, w2, wB0);
;     wA1 = dot2bf(tA.w, w3, wA1); wB1 = dot2bf(tB.w, w3, wB1);
;     aA0 = dot2bf(uA.x, u0, aA0); aB0 = dot2bf(uB.x, u0, aB0);
;     aA1 = dot2bf(uA.y, u1, aA1); aB1 = dot2bf(uB.y, u1, aB1);
;     aA0 = dot2bf(uA.z, u2, aA0); aB0 = dot2bf(uB.z, u2, aB0);
;     aA1 = dot2bf(uA.w, u3, aA1); aB1 = dot2bf(uB.w, u3, aB1);
;   }
.LBB0_584:
	v_cmp_ne_u32_e32 vcc, v165, v30
	v_lshlrev_b32_e32 v141, 16, v141
	v_lshlrev_b32_e32 v137, 16, v137
	v_cndmask_b32_e32 v143, 1.0, v4, vcc
	v_and_b32_e32 v4, 1, v145
	v_mul_lo_u32 v194, v165, s65
	v_mad_u32_u24 v194, v4, s97, v194
	v_lshlrev_b32_e32 v4, 16, v142
	v_lshlrev_b32_e32 v142, 16, v144
	v_fma_f32 v4, v146, v4, -v141
	v_fma_f32 v142, v147, v142, -v141
	v_fmac_f32_e32 v141, v14, v4
	v_fmac_f32_e32 v141, v16, v142
	v_lshlrev_b32_e32 v142, 16, v160
	v_lshlrev_b32_e32 v4, 16, v163
	v_lshlrev_b32_e32 v144, 16, v164
	v_fma_f32 v4, v148, v4, -v142
	v_fma_f32 v144, v149, v144, -v142
	v_fmac_f32_e32 v142, v14, v4
	v_lshlrev_b32_e32 v4, 16, v138
	v_lshlrev_b32_e32 v138, 16, v140
	v_fma_f32 v4, v146, v4, -v137
	v_fma_f32 v138, v147, v138, -v137
	v_fmac_f32_e32 v137, v15, v4
	v_fmac_f32_e32 v137, v17, v138
	v_lshlrev_b32_e32 v138, 16, v158
	v_lshlrev_b32_e32 v4, 16, v161
	v_lshlrev_b32_e32 v140, 16, v162
	v_fma_f32 v4, v148, v4, -v138
	v_fma_f32 v140, v149, v140, -v138
	v_fmac_f32_e32 v138, v15, v4
	v_lshlrev_b32_e32 v134, 16, v134
	v_lshlrev_b32_e32 v4, 16, v135
	v_lshlrev_b32_e32 v135, 16, v139
	v_fma_f32 v4, v146, v4, -v134
	v_fma_f32 v135, v147, v135, -v134
	v_fmac_f32_e32 v134, v18, v4
	v_fmac_f32_e32 v134, v19, v135
	v_lshlrev_b32_e32 v135, 16, v153
	v_lshlrev_b32_e32 v4, 16, v155
	v_lshlrev_b32_e32 v139, 16, v157
	v_fma_f32 v4, v148, v4, -v135
	v_fma_f32 v139, v149, v139, -v135
	v_fmac_f32_e32 v135, v18, v4
	v_lshlrev_b32_e32 v4, 16, v11
	v_lshlrev_b32_e32 v11, 16, v13
	v_lshlrev_b32_e32 v13, 16, v136
	v_fma_f32 v11, v146, v11, -v4
	v_fma_f32 v13, v147, v13, -v4
	v_fmac_f32_e32 v4, v20, v11
	v_fmac_f32_e32 v4, v21, v13
	v_add_f32_e32 v4, v4, v4
	v_mul_f32_e32 v4, 0x3fb8aa3b, v4
	v_lshlrev_b32_e32 v5, 16, v5
	v_lshlrev_b32_e32 v6, 16, v6
	v_exp_f32_e32 v4, v4
	v_lshlrev_b32_e32 v7, 16, v7
	v_fma_f32 v6, v146, v6, -v5
	v_lshlrev_b32_e32 v11, 16, v151
	v_lshlrev_b32_e32 v13, 16, v154
	v_fma_f32 v7, v147, v7, -v5
	v_fmac_f32_e32 v5, v22, v6
	v_lshlrev_b32_e32 v136, 16, v159
	v_fma_f32 v13, v148, v13, -v11
	v_fmac_f32_e32 v5, v23, v7
	v_lshlrev_b32_e32 v6, 16, v150
	v_lshlrev_b32_e32 v7, 16, v152
	v_fma_f32 v136, v149, v136, -v11
	v_fmac_f32_e32 v11, v20, v13
	v_lshlrev_b32_e32 v13, 16, v156
	v_fma_f32 v7, v148, v7, -v6
	v_add_f32_e32 v4, 1.0, v4
	v_fma_f32 v13, v149, v13, -v6
	v_fmac_f32_e32 v6, v22, v7
	v_fmac_f32_e32 v6, v23, v13
	v_fmac_f32_e32 v11, v21, v136
	v_fmac_f32_e32 v135, v19, v139
	v_fmac_f32_e32 v138, v17, v140
	v_rcp_f32_e32 v4, v4
	v_add_f32_e32 v7, v11, v11
	v_mul_f32_e32 v7, 0x3fb8aa3b, v7
	v_exp_f32_e32 v7, v7
	v_fma_f32 v4, v4, -2.0, 1.0
	v_fmac_f32_e32 v142, v16, v144
	v_add_f32_e32 v7, 1.0, v7
	v_cvt_pk_bf16_f32 v4, v4, s0
	ds_write_b16 v97, v4 offset:49152
	v_cvt_pk_bf16_f32 v4, v5, s0
	v_rcp_f32_e32 v7, v7
	s_nop 0
	v_fma_f32 v7, v7, -2.0, 1.0
	ds_write_b16 v97, v4 offset:49280
	v_cvt_pk_bf16_f32 v4, v7, s0
	ds_write_b16 v97, v4 offset:49408
	v_cvt_pk_bf16_f32 v4, v6, s0
	ds_write_b16 v97, v4 offset:49536
	ds_read_b128 v[146:149], v92 offset:49152
	ds_read_b128 v[150:153], v92 offset:49216
	ds_read_b128 v[154:157], v92 offset:49280
	ds_read_b128 v[158:161], v92 offset:49344
	s_waitcnt lgkmcnt(3)
	v_mfma_f32_16x16x32_bf16 v[178:181], v[146:149], v[32:35], 0
	v_mfma_f32_16x16x32_bf16 v[182:185], v[146:149], v[36:39], 0
	v_mfma_f32_16x16x32_bf16 v[186:189], v[146:149], v[40:43], 0
	v_mfma_f32_16x16x32_bf16 v[190:193], v[146:149], v[44:47], 0
	s_waitcnt lgkmcnt(2)
	v_mfma_f32_16x16x32_bf16 v[178:181], v[150:153], v[48:51], v[178:181]
	v_mfma_f32_16x16x32_bf16 v[182:185], v[150:153], v[52:55], v[182:185]
	v_mfma_f32_16x16x32_bf16 v[186:189], v[150:153], v[56:59], v[186:189]
	v_mfma_f32_16x16x32_bf16 v[190:193], v[150:153], v[60:63], v[190:193]
	s_waitcnt lgkmcnt(1)
	v_mfma_f32_16x16x32_bf16 v[214:217], v[154:157], v[64:67], 0
	v_mfma_f32_16x16x32_bf16 v[218:221], v[154:157], v[68:71], 0
	v_mfma_f32_16x16x32_bf16 v[222:225], v[154:157], v[72:75], 0
	v_mfma_f32_16x16x32_bf16 v[226:229], v[154:157], v[76:79], 0
	s_waitcnt lgkmcnt(0)
	v_mfma_f32_16x16x32_bf16 v[214:217], v[158:161], v[80:83], v[214:217]
	v_mfma_f32_16x16x32_bf16 v[218:221], v[158:161], v[84:87], v[218:221]
	v_mfma_f32_16x16x32_bf16 v[222:225], v[158:161], v[88:91], v[222:225]
	v_mfma_f32_16x16x32_bf16 v[226:229], v[158:161], v[210:213], v[226:229]
	v_add_u32_e32 v117, 2, v165
	v_cmp_ge_i32_e64 s[10:11], v117, v96
	s_movk_i32 s0, 0x8f
	s_nop 0
	v_addc_co_u32_e64 v119, vcc, 0, v145, s[10:11]
	v_cndmask_b32_e64 v117, v117, v30, s[10:11]
	v_cmp_gt_u32_e32 vcc, s93, v119
	v_cmp_lt_u32_e64 s[12:13], s0, v119
	s_and_saveexec_b64 s[30:31], vcc
	s_cbranch_execz .LBB0_601
	v_lshl_add_u32 v114, v119, 4, v117
	v_cmp_lt_i32_e32 vcc, s95, v114
	s_and_saveexec_b64 s[0:1], vcc
	s_xor_b64 s[14:15], exec, s[0:1]
	s_cbranch_execz .LBB0_590
	s_and_b64 vcc, exec, s[6:7]
	s_mov_b64 s[16:17], -1
	s_cbranch_vccnz .LBB0_588
	v_sub_u32_e32 v1, 0x8ff, v114
	s_mov_b64 s[16:17], 0

; DEV void prep_compute2(PRef p, const PrepConst& pc, const PrepRaw& rwA, const PrepRaw& rwB, int h, int d,
;                        ScanRec* rcA, ScanRec* rcB, float* stw, int lane, float& Dprev) {
;     ...
;   float zzA = -(wA0 + wA1), zzB = -(wB0 + wB1);
;   float spA = zzA > 20.f ? zzA : __logf(1.f + __expf(zzA));
;   float spB = zzB > 20.f ? zzB : __logf(1.f + __expf(zzB));
;   float decA = __expf(-__expf(-spA - 0.5f)), decB = __expf(-__expf(-spB - 0.5f));
;   float aA = __fdividef(1.f, 1.f + __expf(-(aA0 + aA1))), aB = __fdividef(1.f, 1.f + __expf(-(aB0 + aB1)));
;   float kkA = valsA[1] * pc.kkc, kkB = valsB[1] * pc.kkc;
;   float ssA = wave_sum(kkA * kkA), ssB = wave_sum(kkB * kkB);
;   kkA *= rsqrtf(fmaxf(ssA, 1e-24f));
;   kkB *= rsqrtf(fmaxf(ssB, 1e-24f));
;   float kdA = valsA[1] * (1.f + (aA - 1.f) * pc.kac), kdB = valsB[1] * (1.f + (aB - 1.f) * pc.kac);
;   float bonA = wave_sum(valsA[0] * kdA * pc.rkc), bonB = wave_sum(valsB[0] * kdB * pc.rkc);
;   float DA = Dprev * decA, DB = DA * decB;
;   float iDA = __fdividef(1.f, DA), iDB = __fdividef(1.f, DB);
;   rcA->w[lane] = DA; rcB->w[lane] = DB;
;   rcA->kk[lane] = kkA * Dprev; rcB->kk[lane] = kkB * DA;
;   rcA->kka[lane] = kkA * aA * iDA; rcB->kka[lane] = kkB * aB * iDB;
;   rcA->kd[lane] = kdA * iDA; rcB->kd[lane] = kdB * iDB;
;   rcA->r[lane] = valsA[0] * DA; rcB->r[lane] = valsB[0] * DB;
;   rcA->v[lane] = valsA[2]; rcB->v[lane] = valsB[2];
;   Dprev = DB;
;   if (lane == 0) {
;     p.SB[(size_t)rwA.row * 16 + d * 8 + h] = bonA;
;     p.SB[(size_t)rwB.row * 16 + d * 8 + h] = bonB;
;   }
.LBB0_601:
	s_or_b64 exec, exec, s[30:31]
	s_and_b64 s[0:1], exec, s[12:13]
	s_or_b64 s[26:27], s[0:1], s[26:27]
	s_nop 1
	s_mov_b64 exec, 0xffff
	ds_write_b64 v93, v[178:179] offset:51232
	ds_write_b64 v93, v[182:183] offset:51360
	ds_write_b64 v93, v[186:187] offset:51488
	ds_write_b64 v93, v[190:191] offset:51616
	s_nop 1
	ds_write_b64 v93, v[214:215] offset:51744
	ds_write_b64 v93, v[218:219] offset:51872
	ds_write_b64 v93, v[222:223] offset:52000
	ds_write_b64 v93, v[226:227] offset:52128
	s_mov_b64 exec, -1
	ds_read_b64 v[148:149], v93 offset:51232
	ds_read_b64 v[146:147], v93 offset:51744
	s_waitcnt lgkmcnt(1)
	v_add_f32_e32 v4, v24, v148
	v_add_f32_e32 v5, v24, v149
	s_waitcnt lgkmcnt(0)
	v_add_f32_e32 v136, v25, v146
	v_add_f32_e32 v11, v25, v147
	s_mov_b32 s1, 0x3f317217
	s_mov_b32 s16, 0x7f800000
	s_mov_b32 s0, 0xc1a00000
	v_mul_f32_e32 v6, 0xbfb8aa3b, v4
	v_exp_f32_e32 v6, v6
	v_cmp_gt_f32_e32 vcc, s0, v4
	v_add_f32_e32 v6, 1.0, v6
	v_cmp_gt_f32_e64 s[12:13], s2, v6
	s_nop 1
	v_cndmask_b32_e64 v7, 0, 32, s[12:13]
	v_ldexp_f32 v6, v6, v7
	v_log_f32_e32 v6, v6
	s_nop 0
	v_mul_f32_e32 v7, 0x3f317217, v6
	v_fma_f32 v7, v6, s1, -v7
	v_fmac_f32_e32 v7, 0x3377d1cf, v6
	v_fmac_f32_e32 v7, 0x3f317217, v6
	v_cmp_lt_f32_e64 s[14:15], |v6|, s16
	s_nop 1
	v_cndmask_b32_e64 v6, v6, v7, s[14:15]
	v_cndmask_b32_e64 v7, 0, v205, s[12:13]
	v_sub_f32_e32 v6, v6, v7
	v_cndmask_b32_e64 v4, v6, -v4, vcc
	v_mul_f32_e32 v6, 0xbfb8aa3b, v5
	v_exp_f32_e32 v6, v6
	v_cmp_gt_f32_e32 vcc, s0, v5
	v_sub_f32_e32 v4, -0.5, v4
	v_add_f32_e32 v6, 1.0, v6
	v_cmp_gt_f32_e64 s[12:13], s2, v6
	v_mul_f32_e32 v4, 0x3fb8aa3b, v4
	v_exp_f32_e32 v4, v4
	v_cndmask_b32_e64 v7, 0, 32, s[12:13]
	v_ldexp_f32 v6, v6, v7
	v_log_f32_e32 v6, v6
	v_mul_f32_e32 v4, 0xbfb8aa3b, v4
	v_exp_f32_e32 v4, v4
	v_mul_f32_e32 v7, 0x3f317217, v6
	v_fma_f32 v7, v6, s1, -v7
	v_fmac_f32_e32 v7, 0x3377d1cf, v6
	v_fmac_f32_e32 v7, 0x3f317217, v6
	v_cmp_lt_f32_e64 s[14:15], |v6|, s16
	s_nop 1
	v_cndmask_b32_e64 v6, v6, v7, s[14:15]
	v_cndmask_b32_e64 v7, 0, v205, s[12:13]
	v_sub_f32_e32 v6, v6, v7
	v_cndmask_b32_e64 v5, v6, -v5, vcc
	v_mul_f32_e32 v6, 0xbfb8aa3b, v136
	v_exp_f32_e32 v6, v6
	v_sub_f32_e32 v5, -0.5, v5
	v_mul_f32_e32 v5, 0x3fb8aa3b, v5
	v_exp_f32_e32 v5, v5
	v_add_f32_e32 v6, 1.0, v6
	v_mul_f32_e32 v5, 0xbfb8aa3b, v5
	v_exp_f32_e32 v5, v5
	v_rcp_f32_e32 v6, v6
	v_mul_f32_e32 v7, 0xbfb8aa3b, v11
	v_exp_f32_e32 v7, v7
	s_nop 0
	v_add_f32_e32 v7, 1.0, v7
	v_rcp_f32_e32 v7, v7
	v_mul_f32_e32 v11, v26, v137
	v_mul_f32_e32 v13, v26, v138
	v_add_f32_e32 v136, -1.0, v6
	v_add_f32_e32 v139, -1.0, v7
	v_mul_f32_e32 v144, v11, v11
	v_mul_f32_e32 v146, v13, v13
	v_fma_f32 v136, v27, v136, 1.0
	v_fma_f32 v139, v27, v139, 1.0
	v_mul_f32_e32 v136, v137, v136
	v_mul_f32_e32 v137, v138, v139
	v_mul_f32_e32 v147, v141, v136
	v_mul_f32_e32 v148, v142, v137
	v_mul_f32_e32 v147, v29, v147
	v_mul_f32_e32 v148, v29, v148
	v_add_f32_dpp v144, v144, v144 quad_perm:[1,0,3,2] row_mask:0xf bank_mask:0xf
	v_add_f32_dpp v146, v146, v146 quad_perm:[1,0,3,2] row_mask:0xf bank_mask:0xf
	v_add_f32_dpp v147, v147, v147 quad_perm:[1,0,3,2] row_mask:0xf bank_mask:0xf
	v_add_f32_dpp v148, v148, v148 quad_perm:[1,0,3,2] row_mask:0xf bank_mask:0xf
	v_add_f32_dpp v144, v144, v144 quad_perm:[2,3,0,1] row_mask:0xf bank_mask:0xf
	v_add_f32_dpp v146, v146, v146 quad_perm:[2,3,0,1] row_mask:0xf bank_mask:0xf
	v_add_f32_dpp v147, v147, v147 quad_perm:[2,3,0,1] row_mask:0xf bank_mask:0xf
	v_add_f32_dpp v148, v148, v148 quad_perm:[2,3,0,1] row_mask:0xf bank_mask:0xf
	v_add_f32_dpp v144, v144, v144 row_half_mirror row_mask:0xf bank_mask:0xf
	v_add_f32_dpp v146, v146, v146 row_half_mirror row_mask:0xf bank_mask:0xf
	v_add_f32_dpp v147, v147, v147 row_half_mirror row_mask:0xf bank_mask:0xf
	v_add_f32_dpp v148, v148, v148 row_half_mirror row_mask:0xf bank_mask:0xf
	v_add_f32_dpp v144, v144, v144 row_mirror row_mask:0xf bank_mask:0xf
	v_add_f32_dpp v146, v146, v146 row_mirror row_mask:0xf bank_mask:0xf
	v_add_f32_dpp v147, v147, v147 row_mirror row_mask:0xf bank_mask:0xf
	v_add_f32_dpp v148, v148, v148 row_mirror row_mask:0xf bank_mask:0xf
	v_add_f32_dpp v144, v144, v144 row_bcast:15 row_mask:0xa bank_mask:0xf
	v_add_f32_dpp v146, v146, v146 row_bcast:15 row_mask:0xa bank_mask:0xf
	v_add_f32_dpp v147, v147, v147 row_bcast:15 row_mask:0xa bank_mask:0xf
	v_add_f32_dpp v148, v148, v148 row_bcast:15 row_mask:0xa bank_mask:0xf
	v_add_f32_dpp v144, v144, v144 row_bcast:31 row_mask:0xc bank_mask:0xf
	v_add_f32_dpp v146, v146, v146 row_bcast:31 row_mask:0xc bank_mask:0xf
	v_add_f32_dpp v147, v147, v147 row_bcast:31 row_mask:0xc bank_mask:0xf
	v_add_f32_dpp v148, v148, v148 row_bcast:31 row_mask:0xc bank_mask:0xf
	v_readlane_b32 s0, v144, 63
	v_readlane_b32 s1, v146, 63
	v_readlane_b32 s14, v147, 63
	v_readlane_b32 s15, v148, 63
	v_mov_b32_e32 v144, s0
	v_mov_b32_e32 v146, s1
	v_max_f32_e32 v144, 0x179abe15, v144
	v_max_f32_e32 v146, 0x179abe15, v146
	v_rsq_f32_e32 v144, v144
	v_rsq_f32_e32 v146, v146
	v_mul_f32_e32 v138, v143, v4
	v_mul_f32_e32 v4, v138, v5
	v_mul_f32_e32 v11, v11, v144
	v_mul_f32_e32 v13, v13, v146
	v_rcp_f32_e32 v5, v138
	v_rcp_f32_e32 v139, v4
	v_mul_f32_e32 v6, v6, v11
	v_mul_f32_e32 v7, v7, v13
	v_mul_f32_e32 v143, v143, v11
	v_lshl_or_b32 v140, v28, 2, v194
	v_mul_f32_e32 v6, v5, v6
	v_mul_f32_e32 v5, v5, v136
	v_mul_f32_e32 v7, v139, v7
	ds_write2st64_b32 v140, v6, v5 offset0:2 offset1:3
	v_mul_f32_e32 v5, v139, v137
	ds_write2st64_b32 v140, v138, v143 offset1:1
	v_mul_f32_e32 v143, v138, v13
	ds_write2st64_b32 v140, v7, v5 offset0:8 offset1:9
	v_mul_f32_e32 v5, v141, v138
	ds_write2st64_b32 v140, v4, v143 offset0:6 offset1:7
	v_mul_f32_e32 v6, v142, v4
	ds_write2st64_b32 v140, v5, v134 offset0:4 offset1:5
	ds_write2st64_b32 v140, v6, v135 offset0:10 offset1:11
	s_and_saveexec_b64 s[12:13], s[8:9]
	s_cbranch_execz .LBB0_603
	v_ashrrev_i32_e32 v11, 31, v10
	v_mov_b32_e32 v13, s14
	v_lshlrev_b64 v[6:7], 6, v[10:11]
	v_lshl_add_u64 v[6:7], s[22:23], 0, v[6:7]
	global_store_dword v[6:7], v13, off
	v_ashrrev_i32_e32 v13, 31, v12
	v_mov_b32_e32 v5, s15
	v_lshlrev_b64 v[6:7], 6, v[12:13]
	v_lshl_add_u64 v[6:7], s[22:23], 0, v[6:7]
	global_store_dword v[6:7], v5, off
